# P4 sliding-window PV step: V^T fragment LDS reads issued three MFMAs ahead (4-deep register ring)
# baseline (speedup 1.0000x reference)
; __device__ __forceinline__ int crow(int r, int hi) { return (r & 3) + 8 * (r >> 2) + 4 * hi; }
; #define MFMA32(a, b, c) __builtin_amdgcn_mfma_f32_32x32x16_bf16((a), (b), (c), 0, 0, 0)
; __device__ __forceinline__ void swa_item(int it, LAS unsigned char* lds, const bf16_t* SQ, const bf16_t* SK, const bf16_t* SV, const float* sinks, bf16_t* MIX, int tid, int wid, int lane) {
;     ...
;         const int hl = tk >> 2, qt = tk & 3, head = kvh * 8 + hh * 4 + hl;
;         const long qrow = rb + pos0 + 32 * qt + x;
;         bf16x8 qf[4];
; #pragma unroll
;         for (int ks = 0; ks < 4; ++ks) qf[ks] = *(const bf16x8*)(SQ + qrow * 1024 + head * 64 + 16 * ks + 8 * hi);
;         f32x16 st[5];
; #pragma unroll
;         for (int t = 0; t < 5; ++t) {
;             int kp = pos0 + 32 * qt - 128 + 32 * t + x; if (kp < 0) kp = 0;
;             const bf16_t* kptr = SK + (rb + kp) * 128 + kvh * 64 + 8 * hi;
;             f32x16 acc = {};
; #pragma unroll
;             for (int ks = 0; ks < 4; ++ks) acc = MFMA32(*(const bf16x8*)(kptr + 16 * ks), qf[ks], acc);
;             st[t] = acc;
;         }
;         const float sink2 = sinks[head] * LOG2E;
;         float mx = sink2;
; #pragma unroll
;         for (int r = 0; r < 16; ++r) { const int kk = crow(r, hi); if (kk <= x || (n == 0)) st[0][r] = -1e30f; if (kk > x) st[4][r] = -1e30f; }
; #pragma unroll
;         for (int t = 1; t < 4; ++t) if (n == 0 && qt + t < 4) {
; #pragma unroll
;             for (int r = 0; r < 16; ++r) st[t][r] = -1e30f; }
.LBB0_1033:
	global_load_dwordx4 v[66:69], v[118:119], off offset:-64
	global_load_dwordx4 v[176:179], v[118:119], off offset:-32
	global_load_dwordx4 v[180:183], v[118:119], off
	global_load_dwordx4 v[82:85], v[118:119], off offset:32
	global_load_dwordx4 v[34:37], v[108:109], off
	global_load_dwordx4 v[38:41], v[108:109], off offset:32
	global_load_dwordx4 v[42:45], v[108:109], off offset:64
	global_load_dwordx4 v[46:49], v[108:109], off offset:96
	global_load_dwordx4 v[70:73], v[110:111], off
	global_load_dwordx4 v[74:77], v[110:111], off offset:32
	global_load_dwordx4 v[78:81], v[110:111], off offset:64
	global_load_dwordx4 v[184:187], v[110:111], off offset:96
	global_load_dwordx4 v[208:211], v[112:113], off
	global_load_dwordx4 v[212:215], v[112:113], off offset:32
	global_load_dwordx4 v[216:219], v[112:113], off offset:64
	global_load_dwordx4 v[220:223], v[112:113], off offset:96
	global_load_dwordx4 v[224:227], v[114:115], off
	global_load_dwordx4 v[228:231], v[114:115], off offset:32
	global_load_dwordx4 v[232:235], v[114:115], off offset:64
	global_load_dwordx4 v[236:239], v[114:115], off offset:96
	global_load_dwordx4 v[240:243], v[116:117], off
	global_load_dwordx4 v[244:247], v[116:117], off offset:32
	global_load_dwordx4 v[248:251], v[116:117], off offset:64
	s_mov_b32 s14, 0x3fb8aa3b
	s_waitcnt vmcnt(18)
	v_mfma_f32_32x32x16_bf16 v[2:17], v[34:37], v[66:69], 0
	s_nop 0
	s_nop 0
	s_waitcnt vmcnt(17)
	v_mfma_f32_32x32x16_bf16 v[2:17], v[38:41], v[176:179], v[2:17]
	s_nop 0
	s_waitcnt vmcnt(16)
	v_mfma_f32_32x32x16_bf16 v[2:17], v[42:45], v[180:183], v[2:17]
	s_nop 0
	s_waitcnt vmcnt(15)
	v_mfma_f32_32x32x16_bf16 v[2:17], v[46:49], v[82:85], v[2:17]
	s_nop 0
	s_waitcnt vmcnt(14)
	v_mfma_f32_32x32x16_bf16 v[18:33], v[70:73], v[66:69], 0
	s_waitcnt vmcnt(13)
	v_mfma_f32_32x32x16_bf16 v[18:33], v[74:77], v[176:179], v[18:33]
	s_nop 0
	s_waitcnt vmcnt(12)
	v_mfma_f32_32x32x16_bf16 v[18:33], v[78:81], v[180:183], v[18:33]
	s_nop 0
	s_waitcnt vmcnt(11)
	v_mfma_f32_32x32x16_bf16 v[18:33], v[184:187], v[82:85], v[18:33]
	s_nop 0
	s_nop 10
	v_cndmask_b32_e64 v195, v19, v173, s[96:97]
	v_cndmask_b32_e64 v196, v18, v173, s[96:97]
	v_cndmask_b32_e64 v193, v21, v173, s[96:97]
	v_cndmask_b32_e64 v194, v20, v173, s[96:97]
	v_cndmask_b32_e64 v191, v23, v173, s[96:97]
	v_cndmask_b32_e64 v192, v22, v173, s[96:97]
	v_cndmask_b32_e64 v188, v25, v173, s[96:97]
	v_cndmask_b32_e64 v189, v24, v173, s[96:97]
	s_waitcnt vmcnt(10)
	v_mfma_f32_32x32x16_bf16 v[50:65], v[208:211], v[66:69], 0
	global_load_dwordx4 v[208:211], v[116:117], off offset:96
	s_nop 0
	s_waitcnt vmcnt(10)
	v_mfma_f32_32x32x16_bf16 v[50:65], v[212:215], v[176:179], v[50:65]
	s_nop 0
	s_waitcnt vmcnt(9)
	v_mfma_f32_32x32x16_bf16 v[50:65], v[216:219], v[180:183], v[50:65]
	s_nop 0
	s_waitcnt vmcnt(8)
	v_mfma_f32_32x32x16_bf16 v[50:65], v[220:223], v[82:85], v[50:65]
	s_nop 0
	s_nop 10
	v_cndmask_b32_e64 v200, v58, v173, s[0:1]
	v_cndmask_b32_e64 v58, v53, v173, s[0:1]
	v_cndmask_b32_e64 v53, v51, v173, s[0:1]
	v_cndmask_b32_e64 v203, v50, v173, s[0:1]
	v_cndmask_b32_e64 v52, v52, v173, s[0:1]
	v_cndmask_b32_e64 v55, v55, v173, s[0:1]
	v_cndmask_b32_e64 v201, v57, v173, s[0:1]
	v_cndmask_b32_e64 v202, v56, v173, s[0:1]
	v_cndmask_b32_e64 v59, v59, v173, s[0:1]
	v_cndmask_b32_e64 v199, v61, v173, s[0:1]
	v_cndmask_b32_e64 v61, v60, v173, s[0:1]
	v_cndmask_b32_e64 v197, v63, v173, s[0:1]
	v_cndmask_b32_e64 v198, v62, v173, s[0:1]
	s_waitcnt vmcnt(7)
	v_mfma_f32_32x32x16_bf16 v[34:49], v[224:227], v[66:69], 0
	s_waitcnt vmcnt(6)
	v_mfma_f32_32x32x16_bf16 v[34:49], v[228:231], v[176:179], v[34:49]
	s_nop 0
	s_waitcnt vmcnt(5)
	v_mfma_f32_32x32x16_bf16 v[34:49], v[232:235], v[180:183], v[34:49]
	s_nop 0
	s_waitcnt vmcnt(4)
	v_mfma_f32_32x32x16_bf16 v[34:49], v[236:239], v[82:85], v[34:49]
	s_nop 0
	s_nop 10
	v_cndmask_b32_e64 v204, v35, v173, s[6:7]
	v_cndmask_b32_e64 v205, v34, v173, s[6:7]
	v_cndmask_b32_e64 v63, v36, v173, s[6:7]
	v_cndmask_b32_e64 v25, v43, v173, s[6:7]
	v_cndmask_b32_e64 v23, v45, v173, s[6:7]
	v_cndmask_b32_e64 v24, v44, v173, s[6:7]
	v_cndmask_b32_e64 v21, v47, v173, s[6:7]
	v_cndmask_b32_e64 v22, v46, v173, s[6:7]
	v_cndmask_b32_e64 v19, v49, v173, s[6:7]
	v_cndmask_b32_e64 v20, v48, v173, s[6:7]
	s_waitcnt vmcnt(3)
	v_mfma_f32_32x32x16_bf16 v[66:81], v[240:243], v[66:69], 0
	s_waitcnt vmcnt(2)
	v_mfma_f32_32x32x16_bf16 v[66:81], v[244:247], v[176:179], v[66:81]
	s_nop 0
	v_cndmask_b32_e64 v186, v27, v173, s[96:97]
	v_cndmask_b32_e64 v187, v26, v173, s[96:97]
	v_cndmask_b32_e64 v184, v29, v173, s[96:97]
	v_cndmask_b32_e64 v185, v28, v173, s[96:97]
	v_cndmask_b32_e64 v29, v39, v173, s[6:7]
	v_cndmask_b32_e64 v27, v41, v173, s[6:7]
	v_cndmask_b32_e64 v28, v40, v173, s[6:7]
	v_cndmask_b32_e64 v26, v42, v173, s[6:7]
	s_waitcnt vmcnt(1)
	v_mfma_f32_32x32x16_bf16 v[66:81], v[248:251], v[180:183], v[66:81]
	s_nop 0
	v_cndmask_b32_e64 v180, v6, v173, s[72:73]
	v_cndmask_b32_e64 v182, v31, v173, s[96:97]
	v_cndmask_b32_e64 v183, v30, v173, s[96:97]
	v_cndmask_b32_e64 v181, v32, v173, s[96:97]
	v_cndmask_b32_e64 v31, v65, v173, s[0:1]
	v_cndmask_b32_e64 v65, v54, v173, s[0:1]
	v_cndmask_b32_e64 v32, v37, v173, s[6:7]
	v_cndmask_b32_e64 v30, v38, v173, s[6:7]
	s_waitcnt vmcnt(0)
; __device__ __forceinline__ int crow(int r, int hi) { return (r & 3) + 8 * (r >> 2) + 4 * hi; }
; __device__ __forceinline__ void swa_item(int it, LAS unsigned char* lds, const bf16_t* SQ, const bf16_t* SK, const bf16_t* SV, const float* sinks, bf16_t* MIX, int tid, int wid, int lane) {
;     ...
;         const float sink2 = sinks[head] * LOG2E;
;         float mx = sink2;
; #pragma unroll
;         for (int r = 0; r < 16; ++r) { const int kk = crow(r, hi); if (kk <= x || (n == 0)) st[0][r] = -1e30f; if (kk > x) st[4][r] = -1e30f; }
; #pragma unroll
;         for (int t = 1; t < 4; ++t) if (n == 0 && qt + t < 4) {
; #pragma unroll
;             for (int r = 0; r < 16; ++r) st[t][r] = -1e30f; }
; #pragma unroll
;         for (int t = 0; t < 5; ++t)
; #pragma unroll
;             for (int r = 0; r < 16; ++r) mx = fmaxf(mx, st[t][r]);
;         mx = fmaxf(mx, __shfl_xor(mx, 32));
;         float sum = 0.f;
; #pragma unroll
;         for (int t = 0; t < 5; ++t)
; #pragma unroll
;             for (int r = 0; r < 16; ++r) { const float p = __builtin_amdgcn_exp2f(st[t][r] - mx); st[t][r] = p; sum += p; }
;         sum += __shfl_xor(sum, 32); sum += __builtin_amdgcn_exp2f(sink2 - mx);
	v_mfma_f32_32x32x16_bf16 v[66:81], v[208:211], v[82:85], v[66:81]
	global_load_dword v82, v89, s[10:11]
	v_cndmask_b32_e64 v176, v2, v173, s[64:65]
	v_cndmask_b32_e64 v177, v3, v173, s[66:67]
	v_cndmask_b32_e64 v178, v4, v173, s[68:69]
	v_cndmask_b32_e64 v179, v5, v173, s[70:71]
	s_nop 6
	v_cndmask_b32_e64 v2, v66, v173, s[2:3]
	v_cndmask_b32_e64 v175, v2, v66, s[4:5]
	v_cndmask_b32_e64 v66, v73, v173, s[28:29]
	v_cndmask_b32_e64 v73, v10, v173, s[80:81]
	v_cndmask_b32_e64 v83, v69, v173, s[12:13]
	v_cndmask_b32_e64 v69, v70, v173, s[16:17]
	v_cndmask_b32_e64 v70, v7, v173, s[74:75]
	v_cndmask_b32_e64 v85, v173, v67, s[4:5]
	v_cndmask_b32_e64 v84, v68, v173, s[8:9]
	v_cndmask_b32_e64 v68, v71, v173, s[20:21]
	v_cndmask_b32_e64 v71, v8, v173, s[76:77]
	v_cndmask_b32_e64 v67, v72, v173, s[24:25]
	v_cndmask_b32_e64 v72, v9, v173, s[78:79]
	v_cndmask_b32_e64 v9, v74, v173, s[34:35]
	v_cndmask_b32_e64 v74, v11, v173, s[82:83]
	v_cndmask_b32_e64 v8, v75, v173, s[38:39]
	v_cndmask_b32_e64 v75, v12, v173, s[84:85]
	v_cndmask_b32_e64 v7, v76, v173, s[42:43]
	v_cndmask_b32_e64 v76, v13, v173, s[86:87]
	v_cndmask_b32_e64 v6, v77, v173, s[46:47]
	v_cndmask_b32_e64 v77, v14, v173, s[88:89]
	v_cndmask_b32_e64 v5, v78, v173, s[50:51]
	v_cndmask_b32_e64 v78, v15, v173, s[90:91]
	v_cndmask_b32_e64 v4, v79, v173, s[54:55]
	v_cndmask_b32_e64 v79, v16, v173, s[92:93]
	v_cndmask_b32_e64 v3, v80, v173, s[58:59]
	v_cndmask_b32_e64 v80, v17, v173, s[94:95]
	v_cndmask_b32_e64 v2, v81, v173, s[62:63]
	v_cndmask_b32_e64 v81, v33, v173, s[96:97]
	v_cndmask_b32_e64 v33, v64, v173, s[0:1]
	s_waitcnt vmcnt(0)
	v_mul_f32_e32 v10, 0x3fb8aa3b, v82
	v_max3_f32 v10, v10, v176, v177
	v_max3_f32 v10, v10, v178, v179
	v_max3_f32 v10, v10, v180, v70
	v_max3_f32 v10, v10, v71, v72
	v_max3_f32 v10, v10, v73, v74
	v_max3_f32 v10, v10, v75, v76
	v_max3_f32 v10, v10, v77, v78
	v_max3_f32 v10, v10, v79, v80
	v_max3_f32 v10, v10, v196, v195
	v_max3_f32 v10, v10, v194, v193
	v_max3_f32 v10, v10, v192, v191
	v_max3_f32 v10, v10, v189, v188
	v_max3_f32 v10, v10, v187, v186
	v_max3_f32 v10, v10, v185, v184
	v_max3_f32 v10, v10, v183, v182
	v_max3_f32 v10, v10, v181, v81
	v_max3_f32 v10, v10, v203, v53
	v_max3_f32 v10, v10, v52, v58
	v_max3_f32 v10, v10, v65, v55
	v_max3_f32 v10, v10, v202, v201
	v_max3_f32 v10, v10, v200, v59
	v_max3_f32 v10, v10, v61, v199
	v_max3_f32 v10, v10, v198, v197
	v_max3_f32 v10, v10, v33, v31
	v_max3_f32 v10, v10, v205, v204
	v_max3_f32 v10, v10, v63, v32
	v_max3_f32 v10, v10, v30, v29
	v_max3_f32 v10, v10, v28, v27
	v_max3_f32 v10, v10, v26, v25
	v_max3_f32 v10, v10, v24, v23
	v_max3_f32 v10, v10, v22, v21
	v_max3_f32 v10, v10, v20, v19
	v_max3_f32 v10, v10, v175, v85
	v_max3_f32 v10, v10, v84, v83
	v_max3_f32 v10, v10, v69, v68
	v_max3_f32 v10, v10, v67, v66
	v_max3_f32 v10, v10, v9, v8
	v_max3_f32 v10, v10, v7, v6
	v_max3_f32 v10, v10, v5, v4
	v_max3_f32 v10, v10, v3, v2
	ds_bpermute_b32 v11, v174, v10
	s_waitcnt lgkmcnt(0)
	v_max_f32_e32 v11, v11, v11
	v_max_f32_e32 v11, v10, v11
	v_sub_f32_e32 v10, v176, v11
	v_exp_f32_e32 v10, v10
	v_sub_f32_e32 v12, v177, v11
	v_exp_f32_e32 v12, v12
	v_sub_f32_e32 v37, v75, v11
	v_add_f32_e32 v13, 0, v10
	v_exp_f32_e32 v38, v37
	v_add_f32_e32 v14, v12, v13
	v_sub_f32_e32 v13, v178, v11
	v_exp_f32_e32 v13, v13
	v_sub_f32_e32 v37, v76, v11
	v_exp_f32_e32 v40, v37
	v_sub_f32_e32 v37, v77, v11
	v_add_f32_e32 v15, v13, v14
	v_sub_f32_e32 v14, v179, v11
	v_exp_f32_e32 v14, v14
	v_exp_f32_e32 v44, v37
	v_sub_f32_e32 v37, v78, v11
	v_exp_f32_e32 v48, v37
	v_add_f32_e32 v16, v14, v15
	v_sub_f32_e32 v15, v180, v11
	v_exp_f32_e32 v15, v15
	v_sub_f32_e32 v37, v79, v11
	v_exp_f32_e32 v56, v37
	v_sub_f32_e32 v37, v80, v11
	v_add_f32_e32 v17, v15, v16
	v_sub_f32_e32 v16, v70, v11
	v_exp_f32_e32 v16, v16
	v_exp_f32_e32 v60, v37
	v_sub_f32_e32 v41, v194, v11
	v_exp_f32_e32 v42, v41
	v_add_f32_e32 v18, v16, v17
	v_sub_f32_e32 v17, v71, v11
	v_exp_f32_e32 v17, v17
	v_sub_f32_e32 v41, v193, v11
	v_exp_f32_e32 v45, v41
	v_sub_f32_e32 v41, v192, v11
	v_add_f32_e32 v34, v17, v18
	v_sub_f32_e32 v18, v72, v11
	v_exp_f32_e32 v18, v18
	v_exp_f32_e32 v50, v41
	v_sub_f32_e32 v41, v191, v11
	v_exp_f32_e32 v54, v41
	v_add_f32_e32 v35, v18, v34
	v_sub_f32_e32 v34, v73, v11
	v_exp_f32_e32 v34, v34
	v_sub_f32_e32 v41, v189, v11
	v_exp_f32_e32 v64, v41
	v_sub_f32_e32 v41, v188, v11
	v_add_f32_e32 v36, v34, v35
	v_sub_f32_e32 v35, v74, v11
	v_exp_f32_e32 v35, v35
	v_exp_f32_e32 v72, v41
	v_sub_f32_e32 v46, v185, v11
	v_exp_f32_e32 v47, v46
	v_add_f32_e32 v36, v35, v36
	v_add_f32_e32 v36, v38, v36
	v_add_f32_e32 v36, v40, v36
	v_add_f32_e32 v36, v44, v36
	v_add_f32_e32 v36, v48, v36
	v_add_f32_e32 v36, v56, v36
	v_add_f32_e32 v37, v60, v36
	v_sub_f32_e32 v36, v196, v11
	v_exp_f32_e32 v36, v36
	v_sub_f32_e32 v46, v184, v11
	v_exp_f32_e32 v51, v46
	v_sub_f32_e32 v46, v183, v11
	v_add_f32_e32 v39, v36, v37
	v_sub_f32_e32 v37, v195, v11
	v_exp_f32_e32 v37, v37
	v_exp_f32_e32 v57, v46
	v_sub_f32_e32 v46, v182, v11
	v_exp_f32_e32 v62, v46
	v_add_f32_e32 v39, v37, v39
	v_add_f32_e32 v39, v42, v39
	v_add_f32_e32 v39, v45, v39
	v_add_f32_e32 v39, v50, v39
	v_add_f32_e32 v39, v54, v39
	v_add_f32_e32 v39, v64, v39
	v_add_f32_e32 v41, v72, v39
	v_sub_f32_e32 v39, v187, v11
	v_exp_f32_e32 v39, v39
	v_sub_f32_e32 v46, v181, v11
	v_exp_f32_e32 v76, v46
	v_sub_f32_e32 v46, v81, v11
	v_add_f32_e32 v43, v39, v41
	v_sub_f32_e32 v41, v186, v11
	v_exp_f32_e32 v41, v41
	v_exp_f32_e32 v80, v46
	v_sub_f32_e32 v52, v52, v11
	v_sub_f32_e32 v33, v33, v11
	v_add_f32_e32 v43, v41, v43
	v_add_f32_e32 v43, v47, v43
	v_add_f32_e32 v43, v51, v43
	v_add_f32_e32 v43, v57, v43
; #define MFMA32(a, b, c) __builtin_amdgcn_mfma_f32_32x32x16_bf16((a), (b), (c), 0, 0, 0)
; __device__ __forceinline__ void swa_item(int it, LAS unsigned char* lds, const bf16_t* SQ, const bf16_t* SK, const bf16_t* SV, const float* sinks, bf16_t* MIX, int tid, int wid, int lane) {
;     ...
;         float sum = 0.f;
; #pragma unroll
;         for (int t = 0; t < 5; ++t)
; #pragma unroll
;             for (int r = 0; r < 16; ++r) { const float p = __builtin_amdgcn_exp2f(st[t][r] - mx); st[t][r] = p; sum += p; }
;         sum += __shfl_xor(sum, 32); sum += __builtin_amdgcn_exp2f(sink2 - mx);
;         const float inv = 1.0f / sum;
;         f32x16 o0 = {}, o1 = {};
; #pragma unroll
;         for (int t = 0; t < 5; ++t)
; #pragma unroll
;             for (int s = 0; s < 2; ++s) {
;                 const bf16x8 pb = pack8(st[t], s);
;                 const int c0 = 32 * (qt + t) + 16 * s + 4 * hi;
;                 o0 = MFMA32(lds_cat_sw<VS>(VT, x, c0), pb, o0); o1 = MFMA32(lds_cat_sw<VS>(VT, 32 + x, c0), pb, o1);
;                 __builtin_amdgcn_sched_barrier(0);
;             }
	v_add_f32_e32 v43, v62, v43
	v_add_f32_e32 v43, v76, v43
	v_add_f32_e32 v46, v80, v43
	v_sub_f32_e32 v43, v203, v11
	v_exp_f32_e32 v43, v43
	v_exp_f32_e32 v182, v33
	v_sub_f32_e32 v31, v31, v11
	v_exp_f32_e32 v184, v31
	v_add_f32_e32 v49, v43, v46
	v_sub_f32_e32 v46, v53, v11
	v_exp_f32_e32 v46, v46
	v_exp_f32_e32 v53, v52
	v_sub_f32_e32 v52, v58, v11
	v_exp_f32_e32 v58, v52
	v_sub_f32_e32 v52, v65, v11
	v_exp_f32_e32 v65, v52
	v_sub_f32_e32 v52, v55, v11
	v_add_f32_e32 v49, v46, v49
	v_exp_f32_e32 v74, v52
	v_sub_f32_e32 v52, v202, v11
	v_add_f32_e32 v49, v53, v49
	v_exp_f32_e32 v177, v52
	v_sub_f32_e32 v52, v201, v11
	v_add_f32_e32 v49, v58, v49
	v_exp_f32_e32 v180, v52
	v_add_f32_e32 v49, v65, v49
	v_add_f32_e32 v49, v74, v49
	v_add_f32_e32 v49, v177, v49
	v_add_f32_e32 v52, v180, v49
	v_sub_f32_e32 v49, v200, v11
	v_exp_f32_e32 v49, v49
	v_sub_f32_e32 v32, v32, v11
	v_exp_f32_e32 v78, v32
	v_sub_f32_e32 v30, v30, v11
	v_add_f32_e32 v55, v49, v52
	v_sub_f32_e32 v52, v59, v11
	v_exp_f32_e32 v52, v52
	v_sub_f32_e32 v59, v61, v11
	v_exp_f32_e32 v61, v59
	v_sub_f32_e32 v59, v199, v11
	v_exp_f32_e32 v70, v59
	v_sub_f32_e32 v59, v198, v11
	v_exp_f32_e32 v77, v59
	v_sub_f32_e32 v59, v197, v11
	v_add_f32_e32 v55, v52, v55
	v_exp_f32_e32 v176, v59
	v_add_f32_e32 v55, v61, v55
	v_add_f32_e32 v55, v70, v55
	v_add_f32_e32 v55, v77, v55
	v_add_f32_e32 v55, v176, v55
	v_add_f32_e32 v33, v182, v55
	v_add_f32_e32 v31, v184, v33
	v_sub_f32_e32 v33, v205, v11
	v_exp_f32_e32 v55, v33
	v_sub_f32_e32 v33, v204, v11
	v_exp_f32_e32 v59, v33
	v_sub_f32_e32 v33, v63, v11
	v_exp_f32_e32 v73, v33
	v_add_f32_e32 v31, v55, v31
	v_exp_f32_e32 v178, v30
	v_sub_f32_e32 v29, v29, v11
	v_add_f32_e32 v31, v59, v31
	v_exp_f32_e32 v181, v29
	v_sub_f32_e32 v28, v28, v11
	v_add_f32_e32 v31, v73, v31
	v_exp_f32_e32 v186, v28
	v_sub_f32_e32 v27, v27, v11
	v_add_f32_e32 v31, v78, v31
	v_exp_f32_e32 v187, v27
	v_sub_f32_e32 v26, v26, v11
	v_add_f32_e32 v30, v178, v31
	v_exp_f32_e32 v63, v26
	v_sub_f32_e32 v25, v25, v11
	v_add_f32_e32 v29, v181, v30
	v_exp_f32_e32 v71, v25
	v_sub_f32_e32 v24, v24, v11
	v_add_f32_e32 v28, v186, v29
	v_exp_f32_e32 v81, v24
	v_sub_f32_e32 v23, v23, v11
	v_add_f32_e32 v27, v187, v28
	v_exp_f32_e32 v179, v23
	v_sub_f32_e32 v22, v22, v11
	v_add_f32_e32 v26, v63, v27
	v_exp_f32_e32 v183, v22
	v_sub_f32_e32 v21, v21, v11
	v_add_f32_e32 v25, v71, v26
	v_exp_f32_e32 v185, v21
	v_sub_f32_e32 v20, v20, v11
	v_add_f32_e32 v24, v81, v25
	v_exp_f32_e32 v189, v20
	v_sub_f32_e32 v19, v19, v11
	v_add_f32_e32 v23, v179, v24
	v_exp_f32_e32 v192, v19
	v_add_f32_e32 v22, v183, v23
	v_add_f32_e32 v21, v185, v22
	v_add_f32_e32 v20, v189, v21
	v_add_f32_e32 v19, v192, v20
	v_sub_f32_e32 v20, v175, v11
	v_exp_f32_e32 v75, v20
	v_sub_f32_e32 v20, v85, v11
	v_exp_f32_e32 v79, v20
	v_sub_f32_e32 v20, v84, v11
	v_exp_f32_e32 v84, v20
	v_sub_f32_e32 v20, v83, v11
	v_exp_f32_e32 v83, v20
	v_sub_f32_e32 v20, v69, v11
	v_add_f32_e32 v19, v75, v19
	v_exp_f32_e32 v85, v20
	v_sub_f32_e32 v20, v68, v11
	v_add_f32_e32 v19, v79, v19
	v_exp_f32_e32 v188, v20
	v_sub_f32_e32 v20, v67, v11
	v_add_f32_e32 v19, v84, v19
	v_exp_f32_e32 v194, v20
	v_sub_f32_e32 v20, v66, v11
	v_add_f32_e32 v19, v83, v19
	v_exp_f32_e32 v195, v20
	v_sub_f32_e32 v9, v9, v11
	v_add_f32_e32 v19, v85, v19
	v_exp_f32_e32 v67, v9
	v_sub_f32_e32 v8, v8, v11
	v_add_f32_e32 v19, v188, v19
	v_exp_f32_e32 v68, v8
	v_sub_f32_e32 v7, v7, v11
	v_add_f32_e32 v19, v194, v19
	v_exp_f32_e32 v69, v7
	v_sub_f32_e32 v6, v6, v11
	v_add_f32_e32 v19, v195, v19
	v_exp_f32_e32 v175, v6
	v_sub_f32_e32 v5, v5, v11
	v_add_f32_e32 v9, v67, v19
	v_exp_f32_e32 v191, v5
	v_sub_f32_e32 v4, v4, v11
	v_add_f32_e32 v8, v68, v9
	v_exp_f32_e32 v193, v4
	v_sub_f32_e32 v3, v3, v11
	v_add_f32_e32 v7, v69, v8
	v_exp_f32_e32 v196, v3
	v_sub_f32_e32 v2, v2, v11
	v_add_f32_e32 v6, v175, v7
	v_exp_f32_e32 v197, v2
	v_add_f32_e32 v5, v191, v6
	v_add_f32_e32 v4, v193, v5
	v_add_f32_e32 v3, v196, v4
	v_add_f32_e32 v2, v197, v3
	ds_bpermute_b32 v3, v174, v2
	v_cvt_pk_bf16_f32 v20, v10, v12
	v_cvt_pk_bf16_f32 v21, v13, v14
	v_cvt_pk_bf16_f32 v22, v15, v16
	v_cvt_pk_bf16_f32 v23, v17, v18
	s_waitcnt lgkmcnt(0)
	v_add_f32_e32 v2, v2, v3
	v_fma_f32 v3, v82, s14, -v11
	v_exp_f32_e32 v3, v3
	s_nop 0
	v_add_f32_e32 v66, v3, v2
	ds_read_b64 v[208:209], v135
	ds_read_b64 v[210:211], v136
	ds_read_b64 v[212:213], v137
	ds_read_b64 v[214:215], v138
	ds_read_b64 v[216:217], v139
	ds_read_b64 v[218:219], v140
	s_waitcnt lgkmcnt(4)
	v_mfma_f32_32x32x16_bf16 v[2:17], v[208:211], v[20:23], 0
	ds_read_b64 v[220:221], v141
	ds_read_b64 v[222:223], v142
	s_waitcnt lgkmcnt(4)
	v_mfma_f32_32x32x16_bf16 v[18:33], v[212:215], v[20:23], 0
	ds_read_b64 v[208:209], v135 offset:64
	ds_read_b64 v[210:211], v143
	v_cvt_pk_bf16_f32 v198, v34, v35
	v_cvt_pk_bf16_f32 v199, v38, v40
	v_cvt_pk_bf16_f32 v200, v44, v48
	v_cvt_pk_bf16_f32 v201, v56, v60
	s_waitcnt lgkmcnt(4)
	s_nop 0
	v_mfma_f32_32x32x16_bf16 v[2:17], v[216:219], v[198:201], v[2:17]
	ds_read_b64 v[212:213], v144
	ds_read_b64 v[214:215], v145
	s_waitcnt lgkmcnt(4)
	v_mfma_f32_32x32x16_bf16 v[18:33], v[220:223], v[198:201], v[18:33]
	ds_read_b64 v[216:217], v146
	ds_read_b64 v[218:219], v147
	v_cvt_pk_bf16_f32 v34, v36, v37
	v_cvt_pk_bf16_f32 v35, v42, v45
	v_cvt_pk_bf16_f32 v36, v50, v54
	v_cvt_pk_bf16_f32 v37, v64, v72
	s_waitcnt lgkmcnt(4)
	s_nop 0
	v_mfma_f32_32x32x16_bf16 v[2:17], v[208:211], v[34:37], v[2:17]
	ds_read_b64 v[220:221], v148
	ds_read_b64 v[222:223], v149
	s_waitcnt lgkmcnt(4)
; __device__ __forceinline__ unsigned cvtpk(float lo, float hi) { f32x2_t v = {lo, hi}; bf16x2_t b = __builtin_convertvector(v, bf16x2_t); return __builtin_bit_cast(unsigned, b); }
; #define MFMA32(a, b, c) __builtin_amdgcn_mfma_f32_32x32x16_bf16((a), (b), (c), 0, 0, 0)
; __device__ __forceinline__ void swa_item(int it, LAS unsigned char* lds, const bf16_t* SQ, const bf16_t* SK, const bf16_t* SV, const float* sinks, bf16_t* MIX, int tid, int wid, int lane) {
;     ...
;         f32x16 o0 = {}, o1 = {};
; #pragma unroll
;         for (int t = 0; t < 5; ++t)
; #pragma unroll
;             for (int s = 0; s < 2; ++s) {
;                 const bf16x8 pb = pack8(st[t], s);
;                 const int c0 = 32 * (qt + t) + 16 * s + 4 * hi;
;                 o0 = MFMA32(lds_cat_sw<VS>(VT, x, c0), pb, o0); o1 = MFMA32(lds_cat_sw<VS>(VT, 32 + x, c0), pb, o1);
;                 __builtin_amdgcn_sched_barrier(0);
;             }
;         bf16_t* op = MIX + qrow * 2048 + 1024 + head * 64 + 4 * hi;
; #pragma unroll
;         for (int g = 0; g < 4; ++g) {
;             u32x2 w0, w1; w0.x = cvtpk(o0[4 * g] * inv, o0[4 * g + 1] * inv); w0.y = cvtpk(o0[4 * g + 2] * inv, o0[4 * g + 3] * inv);
;             w1.x = cvtpk(o1[4 * g] * inv, o1[4 * g + 1] * inv); w1.y = cvtpk(o1[4 * g + 2] * inv, o1[4 * g + 3] * inv);
;             *(u32x2*)(op + 8 * g) = w0; *(u32x2*)(op + 32 + 8 * g) = w1;
;         }
	v_mfma_f32_32x32x16_bf16 v[18:33], v[212:215], v[34:37], v[18:33]
	ds_read_b64 v[208:209], v135 offset:128
	ds_read_b64 v[210:211], v152
	v_cvt_pk_bf16_f32 v34, v39, v41
	v_cvt_pk_bf16_f32 v35, v47, v51
	v_cvt_pk_bf16_f32 v36, v57, v62
	v_cvt_pk_bf16_f32 v37, v76, v80
	s_waitcnt lgkmcnt(4)
	s_nop 0
	v_mfma_f32_32x32x16_bf16 v[2:17], v[216:219], v[34:37], v[2:17]
	ds_read_b64 v[212:213], v153
	ds_read_b64 v[214:215], v154
	s_waitcnt lgkmcnt(4)
	v_mfma_f32_32x32x16_bf16 v[18:33], v[220:223], v[34:37], v[18:33]
	ds_read_b64 v[216:217], v155
	ds_read_b64 v[218:219], v156
	v_cvt_pk_bf16_f32 v34, v43, v46
	v_cvt_pk_bf16_f32 v35, v53, v58
	v_cvt_pk_bf16_f32 v36, v65, v74
	v_cvt_pk_bf16_f32 v37, v177, v180
	s_waitcnt lgkmcnt(4)
	s_nop 0
	v_mfma_f32_32x32x16_bf16 v[2:17], v[208:211], v[34:37], v[2:17]
	ds_read_b64 v[220:221], v157
	ds_read_b64 v[222:223], v158
	s_waitcnt lgkmcnt(4)
	v_mfma_f32_32x32x16_bf16 v[18:33], v[212:215], v[34:37], v[18:33]
	ds_read_b64 v[208:209], v135 offset:192
	ds_read_b64 v[210:211], v159
	v_cvt_pk_bf16_f32 v34, v49, v52
	v_cvt_pk_bf16_f32 v35, v61, v70
	v_cvt_pk_bf16_f32 v36, v77, v176
	v_cvt_pk_bf16_f32 v37, v182, v184
	s_waitcnt lgkmcnt(4)
	s_nop 0
	v_mfma_f32_32x32x16_bf16 v[2:17], v[216:219], v[34:37], v[2:17]
	ds_read_b64 v[212:213], v160
	ds_read_b64 v[214:215], v161
	s_waitcnt lgkmcnt(4)
	v_mfma_f32_32x32x16_bf16 v[18:33], v[220:223], v[34:37], v[18:33]
	ds_read_b64 v[216:217], v162
	ds_read_b64 v[218:219], v163
	v_cvt_pk_bf16_f32 v34, v55, v59
	v_cvt_pk_bf16_f32 v35, v73, v78
	v_cvt_pk_bf16_f32 v36, v178, v181
	v_cvt_pk_bf16_f32 v37, v186, v187
	s_waitcnt lgkmcnt(4)
	s_nop 0
	v_mfma_f32_32x32x16_bf16 v[2:17], v[208:211], v[34:37], v[2:17]
	ds_read_b64 v[220:221], v164
	ds_read_b64 v[222:223], v165
	s_waitcnt lgkmcnt(4)
	v_mfma_f32_32x32x16_bf16 v[18:33], v[212:215], v[34:37], v[18:33]
	ds_read_b64 v[208:209], v135 offset:256
	ds_read_b64 v[210:211], v166
	v_cvt_pk_bf16_f32 v34, v63, v71
	v_cvt_pk_bf16_f32 v35, v81, v179
	v_cvt_pk_bf16_f32 v36, v183, v185
	v_cvt_pk_bf16_f32 v37, v189, v192
	s_waitcnt lgkmcnt(4)
	s_nop 0
	v_mfma_f32_32x32x16_bf16 v[2:17], v[216:219], v[34:37], v[2:17]
	ds_read_b64 v[212:213], v167
	ds_read_b64 v[214:215], v168
	s_waitcnt lgkmcnt(4)
	v_mfma_f32_32x32x16_bf16 v[18:33], v[220:223], v[34:37], v[18:33]
	ds_read_b64 v[216:217], v169
	ds_read_b64 v[218:219], v170
	v_cvt_pk_bf16_f32 v34, v75, v79
	v_cvt_pk_bf16_f32 v35, v84, v83
	v_cvt_pk_bf16_f32 v36, v85, v188
	v_cvt_pk_bf16_f32 v37, v194, v195
	s_waitcnt lgkmcnt(4)
	s_nop 0
	v_mfma_f32_32x32x16_bf16 v[2:17], v[208:211], v[34:37], v[2:17]
	ds_read_b64 v[220:221], v171
	ds_read_b64 v[222:223], v172
	s_waitcnt lgkmcnt(4)
	v_mfma_f32_32x32x16_bf16 v[18:33], v[212:215], v[34:37], v[18:33]
	v_cvt_pk_bf16_f32 v34, v67, v68
	v_cvt_pk_bf16_f32 v35, v69, v175
	v_cvt_pk_bf16_f32 v36, v191, v193
	v_cvt_pk_bf16_f32 v37, v196, v197
	s_waitcnt lgkmcnt(2)
	s_nop 0
	v_mfma_f32_32x32x16_bf16 v[2:17], v[216:219], v[34:37], v[2:17]
	s_waitcnt lgkmcnt(0)
	v_mfma_f32_32x32x16_bf16 v[18:33], v[220:223], v[34:37], v[18:33]
	v_div_scale_f32 v34, s[40:41], v66, v66, 1.0
	v_rcp_f32_e32 v35, v34
	s_add_u32 s10, s10, 8
	s_addc_u32 s11, s11, 0
	v_lshl_add_u64 v[118:119], v[118:119], 0, s[30:31]
	v_fma_f32 v36, -v34, v35, 1.0
	v_fmac_f32_e32 v35, v36, v35
	v_div_scale_f32 v36, vcc, 1.0, v66, 1.0
	v_mul_f32_e32 v37, v36, v35
	v_fma_f32 v38, -v34, v37, v36
	v_fmac_f32_e32 v37, v38, v35
	v_fma_f32 v34, -v34, v37, v36
	v_div_fmas_f32 v34, v34, v35, v37
	v_div_fixup_f32 v34, v34, v66, 1.0
	v_pk_mul_f32 v[2:3], v[2:3], v[34:35] op_sel_hi:[1,0]
	v_pk_mul_f32 v[4:5], v[4:5], v[34:35] op_sel_hi:[1,0]
	v_cvt_pk_bf16_f32 v2, v2, v3
	v_cvt_pk_bf16_f32 v3, v4, v5
	v_pk_mul_f32 v[4:5], v[18:19], v[34:35] op_sel_hi:[1,0]
	v_pk_mul_f32 v[18:19], v[20:21], v[34:35] op_sel_hi:[1,0]
	v_cvt_pk_bf16_f32 v4, v4, v5
	v_cvt_pk_bf16_f32 v5, v18, v19
	global_store_dwordx2 v[120:121], v[2:3], off offset:-64
	global_store_dwordx2 v[120:121], v[4:5], off
	v_pk_mul_f32 v[2:3], v[6:7], v[34:35] op_sel_hi:[1,0]
	v_pk_mul_f32 v[4:5], v[8:9], v[34:35] op_sel_hi:[1,0]
	v_cvt_pk_bf16_f32 v2, v2, v3
	v_cvt_pk_bf16_f32 v3, v4, v5
	v_pk_mul_f32 v[4:5], v[22:23], v[34:35] op_sel_hi:[1,0]
	v_pk_mul_f32 v[6:7], v[24:25], v[34:35] op_sel_hi:[1,0]
	v_cvt_pk_bf16_f32 v4, v4, v5
	v_cvt_pk_bf16_f32 v5, v6, v7
	global_store_dwordx2 v[120:121], v[2:3], off offset:-48
	global_store_dwordx2 v[120:121], v[4:5], off offset:16
	v_pk_mul_f32 v[2:3], v[10:11], v[34:35] op_sel_hi:[1,0]
	v_pk_mul_f32 v[4:5], v[12:13], v[34:35] op_sel_hi:[1,0]
	v_cvt_pk_bf16_f32 v2, v2, v3
	v_cvt_pk_bf16_f32 v3, v4, v5
	v_pk_mul_f32 v[4:5], v[26:27], v[34:35] op_sel_hi:[1,0]
	v_pk_mul_f32 v[6:7], v[28:29], v[34:35] op_sel_hi:[1,0]
	v_cvt_pk_bf16_f32 v4, v4, v5
	v_cvt_pk_bf16_f32 v5, v6, v7
	global_store_dwordx2 v[120:121], v[2:3], off offset:-32
	global_store_dwordx2 v[120:121], v[4:5], off offset:32
	v_pk_mul_f32 v[2:3], v[14:15], v[34:35] op_sel_hi:[1,0]
	v_pk_mul_f32 v[4:5], v[16:17], v[34:35] op_sel_hi:[1,0]
	v_cvt_pk_bf16_f32 v2, v2, v3
	v_cvt_pk_bf16_f32 v3, v4, v5
	v_pk_mul_f32 v[4:5], v[30:31], v[34:35] op_sel_hi:[1,0]
	v_pk_mul_f32 v[6:7], v[32:33], v[34:35] op_sel_hi:[1,0]
	v_add_co_u32_e32 v88, vcc, 8, v88
	v_cvt_pk_bf16_f32 v4, v4, v5
	v_cvt_pk_bf16_f32 v5, v6, v7
	global_store_dwordx2 v[120:121], v[2:3], off offset:-16
	global_store_dwordx2 v[120:121], v[4:5], off offset:48
	v_lshl_add_u64 v[120:121], v[120:121], 0, s[30:31]
	s_and_b64 vcc, exec, vcc
	s_cbranch_vccnz .LBB0_1033
	v_readlane_b32 s64, v254, 36
	v_readlane_b32 s72, v254, 44
	v_readlane_b32 s73, v254, 45
	v_readlane_b32 s74, v254, 46
	v_readlane_b32 s75, v254, 47
	v_readlane_b32 s76, v254, 48
	v_readlane_b32 s77, v254, 49
	v_readlane_b32 s78, v254, 50
	v_readlane_b32 s79, v254, 51
	v_readlane_b32 s88, v255, 38
	v_readlane_b32 s68, v254, 40
	v_readlane_b32 s69, v254, 41
	v_readlane_b32 s70, v254, 42
	v_readlane_b32 s71, v254, 43
	s_mov_b64 s[82:83], s[78:79]
	s_mov_b64 s[96:97], s[52:53]
	v_readlane_b32 s52, v255, 42
	s_mov_b64 s[84:85], s[22:23]
	s_mov_b32 s86, s61
	v_readlane_b32 s89, v255, 39
	s_mov_b32 s87, s26
	s_mov_b64 s[80:81], s[76:77]
	s_mov_b64 s[78:79], s[74:75]
	s_mov_b64 s[76:77], s[72:73]
	s_mov_b64 s[74:75], s[70:71]
	s_mov_b64 s[72:73], s[68:69]
	s_mov_b64 s[94:95], s[36:37]
	s_mov_b64 s[36:37], s[18:19]
	v_readlane_b32 s53, v255, 43
	v_readlane_b32 s90, v255, 40
	v_readlane_b32 s91, v255, 41
	v_readlane_b32 s65, v254, 37
	v_readlane_b32 s66, v254, 38
	v_readlane_b32 s67, v254, 39
	s_branch .LBB0_1022
